# v11 + prompt attention fast tile path: distance bias via MFMA C operand + per-lane shift folded into running max (non-diagonal tiles), hand-written softmax/PV block
# speedup vs baseline: 1.0117x; 1.0032x over previous
; #define GASP __attribute__((address_space(1)))
;     ...
;     const int S = SAMPLE ? PAST + DECS : SEQ, qpos0 = SAMPLE ? PAST : qi * 128 + sub * 32, rowq0 = SAMPLE ? NP + b * 32 : b * SEQ + qi * 128 + sub * 32;
;     const int NT = SAMPLE ? (PAST + DECS + 63) / 64 : 2 * qi + 2;
;     const int ntw = SAMPLE ? NT : min(NT, (qpos0 >> 6) + 1);
;     const float slope2 = exp2f(-2.f * (float)(h + 1)) * LOG2E;
;     bf16x8 qf[4];
;     { const bf16_t* qp = QB + (size_t)(rowq0 + r) * 512 + h * 128 + map * 64 + hi * 8;
; #pragma unroll
;       for (int d0 = 0; d0 < 4; ++d0) qf[d0] = *(const GASP bf16x8*)(qp + d0 * 16); }
;     f32x16 OT[NEB];
; #pragma unroll
;     for (int e = 0; e < NEB; ++e)
; #pragma unroll
;         for (int i = 0; i < 16; ++i) OT[e][i] = 0.f;
;     float m = -1e30f, l = 0.f;
;     const int lkey = tid >> 3, lc = tid & 7;
;     u32x4 pfA[NPF], pfB[SAMPLE ? 1 : NPF];
;     const float* ck = p.in[2]; const float* cv = p.in[3];
;     ...
;     const int i16 = lane & 15;
;     const int vlane_off = (4 * hi + (i16 >> 2)) * DA_VRS + (16 * ((lane >> 4) & 1) + 4 * (i16 & 3)) * 2;
;     const int tq = qpos0 + r;
;     ...
;     DA_ISSUE(pfA, 0); DA_WRITE(pfA, 0, 0);
;     if constexpr (SAMPLE) {
;         asm volatile("" : "+v"(qf[0]), "+v"(qf[1]), "+v"(qf[2]), "+v"(qf[3]));
;         __syncthreads();
; #pragma unroll 1
;         for (int tt = 0; tt < NT; ++tt) {
;             if (tt + 1 < NT) DA_ISSUE(pfA, tt + 1);
;             DA_COMPUTE(tt, tt & 1);
;             if (tt + 1 < NT) DA_WRITE(pfA, tt + 1, (tt + 1) & 1);
;             __syncthreads();
;         }
;     } else {
;     if (NT > 1) DA_ISSUE(pfA, 1);
;     asm volatile("" : "+v"(qf[0]), "+v"(qf[1]), "+v"(qf[2]), "+v"(qf[3]));
;     __syncthreads();
.LBB0_923:
	s_add_i32 s5, s4, 0xffffff80
	s_waitcnt vmcnt(11)
	v_mov_b32_e32 v24, v208
	s_lshr_b32 s6, s5, 6
	s_sub_i32 s7, 15, s6
	v_readfirstlane_b32 s8, v24
	s_bfe_u32 s10, s8, 0x20006
	s_lshl_b32 s5, s7, 7
	s_lshl_b32 s15, s10, 5
	s_or_b32 s28, s15, s5
	s_lshl_b32 s5, s4, 9
	v_and_b32_e32 v149, 31, v24
	s_and_b32 s11, s5, 0x7800
	s_and_b32 s14, s4, 3
	v_or_b32_e32 v0, s11, v149
	v_ashrrev_i32_e32 v25, 3, v24
	v_or_b32_e32 v146, s28, v0
	s_lshl_b32 s5, s14, 7
	s_waitcnt vmcnt(10)
	v_and_b32_e32 v26, 7, v24
	s_waitcnt vmcnt(4)
	v_add_u32_e32 v20, s11, v25
	s_ashr_i32 s9, s8, 8
	v_lshlrev_b32_e32 v0, 10, v146
	v_ashrrev_i32_e32 v21, 31, v20
	v_lshl_or_b32 v148, v26, 4, s5
	v_lshl_add_u64 v[2:3], s[70:71], 0, v[0:1]
	s_lshl_b32 s30, s14, 8
	s_lshl_b32 s12, s9, 6
	v_lshlrev_b64 v[10:11], 10, v[20:21]
	v_lshlrev_b32_e32 v21, 1, v148
	v_bfe_u32 v152, v24, 5, 1
	v_lshl_add_u64 v[2:3], v[2:3], 0, s[30:31]
	s_ashr_i32 s13, s12, 31
	v_or_b32_e32 v10, v10, v21
	v_lshl_add_u64 v[2:3], s[12:13], 1, v[2:3]
	v_lshlrev_b32_e32 v0, 4, v152
	v_lshl_add_u64 v[6:7], s[72:73], 0, v[10:11]
	v_lshl_add_u64 v[18:19], v[2:3], 0, v[0:1]
	global_load_dwordx4 v[2:5], v[6:7], off offset:16
	s_nop 0
	global_load_dwordx4 v[6:9], v[6:7], off
	s_waitcnt vmcnt(2)
	v_lshl_add_u64 v[14:15], s[74:75], 0, v[10:11]
	global_load_dwordx4 v[10:13], v[14:15], off offset:16
	s_nop 0
	global_load_dwordx4 v[14:17], v[14:15], off
	s_nop 0
	global_load_dwordx4 v[98:101], v[18:19], off offset:96
	global_load_dwordx4 v[102:105], v[18:19], off offset:64
	global_load_dwordx4 v[106:109], v[18:19], off offset:32
	global_load_dwordx4 v[110:113], v[18:19], off
	v_add_u32_e32 v18, 64, v20
	v_ashrrev_i32_e32 v19, 31, v18
	v_lshlrev_b64 v[18:19], 10, v[18:19]
	v_or_b32_e32 v18, v18, v21
	v_lshl_add_u64 v[22:23], s[74:75], 0, v[18:19]
	v_lshl_add_u64 v[18:19], s[72:73], 0, v[18:19]
	global_load_dwordx4 v[122:125], v[22:23], off offset:16
	global_load_dwordx4 v[126:129], v[22:23], off
	global_load_dwordx4 v[114:117], v[18:19], off offset:16
	global_load_dwordx4 v[118:121], v[18:19], off
	s_not_b32 s12, s14
	s_lshl_b32 s13, s12, 1
	v_and_b32_e32 v19, 16, v24
	v_lshlrev_b32_e32 v21, 2, v24
	v_bfe_u32 v22, v24, 2, 1
	s_lshl_b32 s12, s7, 1
	s_lshr_b32 s7, s28, 6
	v_lshrrev_b32_e32 v18, 2, v24
	v_lshlrev_b32_e32 v23, 5, v24
	v_ldexp_f32 v24, 1.0, s13
	v_and_or_b32 v19, v21, 12, v19
	v_mul_u32_u24_e32 v21, 0x2400, v22
	v_mul_lo_u32 v22, v25, s90
	s_add_i32 s13, s12, 2
	s_add_i32 s7, s7, 1
	v_lshlrev_b32_e32 v147, 2, v152
	v_and_b32_e32 v23, 0x60, v23
	v_mul_lo_u32 v25, v25, s88
	v_add3_u32 v21, 0, v21, v22
	s_min_u32 s14, s13, s7
	s_mul_i32 s7, s9, 0x2400
	v_lshlrev_b32_e32 v26, 5, v26
	v_and_or_b32 v18, v18, 3, v147
	v_add_u32_e32 v22, 0, v25
	v_add_u32_e32 v154, v21, v23
	s_add_i32 s7, s7, 0
	v_mul_u32_u24_e32 v18, 0x140, v18
	v_add_u32_e32 v155, v22, v26
	v_lshl_or_b32 v18, v19, 1, v18
	s_lshl_b32 s6, s6, 7
	v_mul_f32_e32 v153, 0x3fb8aa3b, v24
	v_add_u32_e32 v156, 0, v18
	v_add_u32_e32 v150, 0xc0, v20
	s_mov_b32 s11, 3
	v_add_u32_e32 v157, 0xe000, v156
	v_mov_b32_e32 v163, 0xf149f2ca
	v_mov_b32_e32 v159, 0
	s_waitcnt vmcnt(10)
	ds_write_b128 v154, v[6:9]
	ds_write_b128 v154, v[2:5] offset:16
	s_waitcnt vmcnt(8)
	ds_write_b128 v155, v[14:17] offset:18432
	ds_write_b128 v155, v[10:13] offset:18448
	v_mov_b32_e32 v2, s7
	v_mad_u32_u24 v19, v149, s90, v2
	v_or_b32_e32 v2, s15, v149
	v_or_b32_e32 v2, 0x780, v2
	v_sub_u32_e32 v2, v2, v147
	v_mov_b32_e32 v16, v1
	v_mov_b32_e32 v17, v1
	v_subrev_u32_e32 v158, s6, v2
	v_mov_b32_e32 v2, v1
	v_mov_b32_e32 v3, v1
	v_mov_b32_e32 v4, v1
	v_mov_b32_e32 v5, v1
	v_mov_b32_e32 v6, v1
	v_mov_b32_e32 v7, v1
	v_mov_b32_e32 v8, v1
	v_mov_b32_e32 v9, v1
	v_mov_b32_e32 v10, v1
	v_mov_b32_e32 v11, v1
	v_mov_b32_e32 v12, v1
	v_mov_b32_e32 v13, v1
	v_mov_b32_e32 v14, v1
	v_mov_b32_e32 v15, v1
	v_add_u32_e32 v162, v19, v0
	v_mov_b64_e32 v[32:33], v[16:17]
	v_mov_b64_e32 v[48:49], v[16:17]
	v_mov_b64_e32 v[64:65], v[16:17]
	v_mov_b64_e32 v[30:31], v[14:15]
	v_mov_b64_e32 v[28:29], v[12:13]
	v_mov_b64_e32 v[26:27], v[10:11]
	v_mov_b64_e32 v[24:25], v[8:9]
	v_mov_b64_e32 v[22:23], v[6:7]
	v_mov_b64_e32 v[20:21], v[4:5]
	v_mov_b64_e32 v[18:19], v[2:3]
	v_mov_b64_e32 v[46:47], v[14:15]
	v_mov_b64_e32 v[44:45], v[12:13]
	v_mov_b64_e32 v[42:43], v[10:11]
	v_mov_b64_e32 v[40:41], v[8:9]
	v_mov_b64_e32 v[38:39], v[6:7]
	v_mov_b64_e32 v[36:37], v[4:5]
	v_mov_b64_e32 v[34:35], v[2:3]
	v_mov_b64_e32 v[62:63], v[14:15]
	v_mov_b64_e32 v[60:61], v[12:13]
	v_mov_b64_e32 v[58:59], v[10:11]
	v_mov_b64_e32 v[56:57], v[8:9]
	v_mov_b64_e32 v[54:55], v[6:7]
	v_mov_b64_e32 v[52:53], v[4:5]
	v_mov_b64_e32 v[50:51], v[2:3]
	v_mov_b32_e32 v210, 0
	v_mul_f32_e32 v211, 1.0, v153
	v_mul_f32_e32 v212, 2.0, v153
	v_mul_f32_e32 v213, 0x40400000, v153
	v_mul_f32_e32 v214, 0x41000000, v153
	v_mul_f32_e32 v215, 0x41100000, v153
	v_mul_f32_e32 v216, 0x41200000, v153
	v_mul_f32_e32 v217, 0x41300000, v153
	v_mul_f32_e32 v218, 0x41800000, v153
	v_mul_f32_e32 v219, 0x41880000, v153
	v_mul_f32_e32 v220, 0x41900000, v153
	v_mul_f32_e32 v221, 0x41980000, v153
	v_mul_f32_e32 v222, 0x41c00000, v153
	v_mul_f32_e32 v223, 0x41c80000, v153
	v_mul_f32_e32 v224, 0x41d00000, v153
	v_mul_f32_e32 v225, 0x41d80000, v153
	v_mul_f32_e32 v226, 0x42000000, v153
	v_mul_f32_e32 v227, 0x42040000, v153
	v_mul_f32_e32 v228, 0x42080000, v153
	v_mul_f32_e32 v229, 0x420c0000, v153
	v_mul_f32_e32 v230, 0x42200000, v153
	v_mul_f32_e32 v231, 0x42240000, v153
	v_mul_f32_e32 v232, 0x42280000, v153
	v_mul_f32_e32 v233, 0x422c0000, v153
	v_mul_f32_e32 v234, 0x42400000, v153
	v_mul_f32_e32 v235, 0x42440000, v153
	v_mul_f32_e32 v236, 0x42480000, v153
	v_mul_f32_e32 v237, 0x424c0000, v153
	v_mul_f32_e32 v238, 0x42600000, v153
	v_mul_f32_e32 v239, 0x42640000, v153
	v_mul_f32_e32 v240, 0x42680000, v153
	v_mul_f32_e32 v241, 0x426c0000, v153
	s_waitcnt vmcnt(4)
	s_waitcnt lgkmcnt(0)
	s_barrier
	s_branch .LBB0_925

; __device__ __forceinline__ float fexp2(float x) { return __builtin_amdgcn_exp2f(x); }
; template <int NEB>
; __device__ __forceinline__ void softmax_tile(f32x16& X0, f32x16& X1, float& m, float& l, f32x16 (&OT)[NEB]) {
;     float mx = X0[0];
; #pragma unroll
;     for (int r = 1; r < 16; ++r) mx = fmaxf(mx, X0[r]);
; #pragma unroll
;     for (int r = 0; r < 16; ++r) mx = fmaxf(mx, X1[r]);
;     mx = fmaxf(mx, __shfl_xor(mx, 32));
;     if (__any(mx > m + 8.f)) {
;         const float mn = fmaxf(m, mx), alpha = fexp2(m - mn); m = mn; l *= alpha;
; #pragma unroll
;         for (int e = 0; e < NEB; ++e) OT[e] = OT[e] * alpha;
;     }
.Lp_e1_skip:
	s_cmp_ge_u32 s15, s14
	s_cbranch_scc1 .LBB0_931
	s_add_i32 s99, s15, 1
	s_cmp_ge_u32 s99, s14
	s_cbranch_scc1 .Lpf0_slow
	ds_read_b128 v[66:69], v162
	ds_read_b128 v[166:169], v162 offset:32
	ds_read_b128 v[82:85], v162 offset:4608
	ds_read_b128 v[176:179], v162 offset:4640
	v_cvt_f32_i32_e32 v186, v158
	s_waitcnt lgkmcnt(3)
	v_mfma_f32_32x32x16_bf16 v[66:81], v[66:69], v[110:113], v[210:225]
	v_mul_f32_e64 v175, -v153, v186
	s_waitcnt lgkmcnt(1)
	v_mfma_f32_32x32x16_bf16 v[82:97], v[82:85], v[110:113], v[226:241]
	v_mfma_f32_32x32x16_bf16 v[66:81], v[166:169], v[106:109], v[66:81]
	s_waitcnt lgkmcnt(0)
	v_mfma_f32_32x32x16_bf16 v[82:97], v[176:179], v[106:109], v[82:97]
	ds_read_b128 v[166:169], v162 offset:64
	ds_read_b128 v[176:179], v162 offset:96
	s_waitcnt lgkmcnt(1)
	v_mfma_f32_32x32x16_bf16 v[66:81], v[166:169], v[102:105], v[66:81]
	ds_read_b128 v[166:169], v162 offset:4672
	ds_read_b128 v[182:185], v162 offset:4704
	s_waitcnt lgkmcnt(1)
	v_mfma_f32_32x32x16_bf16 v[82:97], v[166:169], v[102:105], v[82:97]
	v_mfma_f32_32x32x16_bf16 v[66:81], v[176:179], v[98:101], v[66:81]
	s_waitcnt lgkmcnt(0)
	v_mfma_f32_32x32x16_bf16 v[82:97], v[182:185], v[98:101], v[82:97]
	ds_read_b64_tr_b16 v[166:167], v156 offset:18432
	ds_read_b64_tr_b16 v[168:169], v156 offset:20992
	ds_read_b64_tr_b16 v[176:177], v156 offset:18496
	ds_read_b64_tr_b16 v[178:179], v156 offset:21056
	ds_read_b64_tr_b16 v[180:181], v156 offset:18560
	ds_read_b64_tr_b16 v[182:183], v156 offset:21120
	ds_read_b64_tr_b16 v[184:185], v156 offset:18624
	ds_read_b64_tr_b16 v[186:187], v156 offset:21184
	s_nop 5
	v_max3_f32 v0, v66, v67, v68
	v_max3_f32 v151, v82, v83, v84
	v_max3_f32 v0, v0, v69, v70
	v_max3_f32 v151, v151, v85, v86
	v_max3_f32 v0, v0, v71, v72
	v_max3_f32 v151, v151, v87, v88
	v_max3_f32 v0, v0, v73, v74
	v_max3_f32 v151, v151, v89, v90
	v_max3_f32 v0, v0, v75, v76
	v_max3_f32 v151, v151, v91, v92
	v_max3_f32 v0, v0, v77, v78
	v_max3_f32 v151, v151, v93, v94
	v_max3_f32 v0, v0, v79, v80
	v_max3_f32 v151, v151, v95, v96
	v_max3_f32 v0, v0, v81, v151
	v_max_f32_e32 v0, v0, v97
	v_add_f32_e32 v0, v0, v175
	ds_bpermute_b32 v164, v171, v0
	s_waitcnt lgkmcnt(0)
	v_max_f32_e32 v0, v0, v164
	v_add_f32_e32 v164, 0x41000000, v163
	v_cmp_gt_f32_e32 vcc, v0, v164
	s_cbranch_vccz .Lpf0_nores
	v_max_f32_e32 v0, v163, v0
	v_sub_f32_e32 v164, v163, v0
	v_exp_f32_e32 v164, v164
	v_mov_b32_e32 v163, v0
	s_nop 0
	v_mul_f32_e32 v159, v159, v164
	v_pk_mul_f32 v[64:65], v[64:65], v[164:165] op_sel_hi:[1,0]
	v_pk_mul_f32 v[62:63], v[62:63], v[164:165] op_sel_hi:[1,0]
	v_pk_mul_f32 v[60:61], v[60:61], v[164:165] op_sel_hi:[1,0]
	v_pk_mul_f32 v[58:59], v[58:59], v[164:165] op_sel_hi:[1,0]
	v_pk_mul_f32 v[56:57], v[56:57], v[164:165] op_sel_hi:[1,0]
	v_pk_mul_f32 v[54:55], v[54:55], v[164:165] op_sel_hi:[1,0]
	v_pk_mul_f32 v[52:53], v[52:53], v[164:165] op_sel_hi:[1,0]
	v_pk_mul_f32 v[50:51], v[50:51], v[164:165] op_sel_hi:[1,0]
	v_pk_mul_f32 v[48:49], v[48:49], v[164:165] op_sel_hi:[1,0]
	v_pk_mul_f32 v[46:47], v[46:47], v[164:165] op_sel_hi:[1,0]
	v_pk_mul_f32 v[44:45], v[44:45], v[164:165] op_sel_hi:[1,0]
	v_pk_mul_f32 v[42:43], v[42:43], v[164:165] op_sel_hi:[1,0]
	v_pk_mul_f32 v[40:41], v[40:41], v[164:165] op_sel_hi:[1,0]
	v_pk_mul_f32 v[38:39], v[38:39], v[164:165] op_sel_hi:[1,0]
	v_pk_mul_f32 v[36:37], v[36:37], v[164:165] op_sel_hi:[1,0]
	v_pk_mul_f32 v[34:35], v[34:35], v[164:165] op_sel_hi:[1,0]
	v_pk_mul_f32 v[32:33], v[32:33], v[164:165] op_sel_hi:[1,0]
	v_pk_mul_f32 v[30:31], v[30:31], v[164:165] op_sel_hi:[1,0]
	v_pk_mul_f32 v[28:29], v[28:29], v[164:165] op_sel_hi:[1,0]
	v_pk_mul_f32 v[26:27], v[26:27], v[164:165] op_sel_hi:[1,0]
	v_pk_mul_f32 v[24:25], v[24:25], v[164:165] op_sel_hi:[1,0]
	v_pk_mul_f32 v[22:23], v[22:23], v[164:165] op_sel_hi:[1,0]
	v_pk_mul_f32 v[20:21], v[20:21], v[164:165] op_sel_hi:[1,0]
	v_pk_mul_f32 v[18:19], v[18:19], v[164:165] op_sel_hi:[1,0]
	v_pk_mul_f32 v[16:17], v[16:17], v[164:165] op_sel_hi:[1,0]
	v_pk_mul_f32 v[14:15], v[14:15], v[164:165] op_sel_hi:[1,0]
	v_pk_mul_f32 v[12:13], v[12:13], v[164:165] op_sel_hi:[1,0]
	v_pk_mul_f32 v[10:11], v[10:11], v[164:165] op_sel_hi:[1,0]
	v_pk_mul_f32 v[8:9], v[8:9], v[164:165] op_sel_hi:[1,0]
	v_pk_mul_f32 v[6:7], v[6:7], v[164:165] op_sel_hi:[1,0]
	v_pk_mul_f32 v[4:5], v[4:5], v[164:165] op_sel_hi:[1,0]
	v_pk_mul_f32 v[2:3], v[2:3], v[164:165] op_sel_hi:[1,0]
; #define LAS __attribute__((address_space(3)))
; __device__ __forceinline__ float fexp2(float x) { return __builtin_amdgcn_exp2f(x); }
; __device__ __forceinline__ s16x4 vtr(const LAS unsigned char* p) { return __builtin_bit_cast(s16x4, __builtin_amdgcn_ds_read_tr16_b64_v4i16((LAS v4i16_t*)p)); }
; __device__ __forceinline__ bf16x8 cat8(s16x4 lo, s16x4 hi) { return (bf16x8){lo[0], lo[1], lo[2], lo[3], hi[0], hi[1], hi[2], hi[3]}; }
; template <int NEB>
; __device__ __forceinline__ void softmax_tile(f32x16& X0, f32x16& X1, float& m, float& l, f32x16 (&OT)[NEB]) {
;     ...
;     float s = 0.f;
; #pragma unroll
;     for (int r = 0; r < 16; ++r) { X0[r] = fexp2(X0[r] - m); X1[r] = fexp2(X1[r] - m); s += X0[r] + X1[r]; }
;     l += s;
; }
; template <int VRS, int NEB, bool SB = false>
; __device__ __forceinline__ void pv_tile(f32x16 (&OT)[NEB], const f32x16& X0, const f32x16& X1, const LAS unsigned char* vlane  ) {
; #pragma unroll
;     for (int kk = 0; kk < 4; ++kk) {
;         const bf16x8 pa = packp(kk < 2 ? X0 : X1, (kk & 1) * 8);
; #pragma unroll
;         for (int eb = 0; eb < NEB; ++eb) {
;             const s16x4 lo = vtr(vlane + (kk * 16) * VRS + eb * 64), hi = vtr(vlane + (kk * 16 + 8) * VRS + eb * 64);
;             OT[eb] = __builtin_amdgcn_mfma_f32_32x32x16_bf16(cat8(lo, hi), pa, OT[eb], 0, 0, 0);
;         }
;         if (SB) __builtin_amdgcn_sched_barrier(0);
;     }
; }
.Lpf0_nores:
	v_sub_f32_e32 v164, v175, v163
	v_pk_add_f32 v[66:67], v[66:67], v[164:165] op_sel_hi:[1,0]
	v_pk_add_f32 v[68:69], v[68:69], v[164:165] op_sel_hi:[1,0]
	v_pk_add_f32 v[70:71], v[70:71], v[164:165] op_sel_hi:[1,0]
	v_pk_add_f32 v[72:73], v[72:73], v[164:165] op_sel_hi:[1,0]
	v_pk_add_f32 v[74:75], v[74:75], v[164:165] op_sel_hi:[1,0]
	v_pk_add_f32 v[76:77], v[76:77], v[164:165] op_sel_hi:[1,0]
	v_pk_add_f32 v[78:79], v[78:79], v[164:165] op_sel_hi:[1,0]
	v_pk_add_f32 v[80:81], v[80:81], v[164:165] op_sel_hi:[1,0]
	v_exp_f32_e32 v66, v66
	v_exp_f32_e32 v67, v67
	v_exp_f32_e32 v68, v68
	v_exp_f32_e32 v69, v69
	v_exp_f32_e32 v70, v70
	v_exp_f32_e32 v71, v71
	v_exp_f32_e32 v72, v72
	v_exp_f32_e32 v73, v73
	v_exp_f32_e32 v74, v74
	v_exp_f32_e32 v75, v75
	v_exp_f32_e32 v76, v76
	v_exp_f32_e32 v77, v77
	v_exp_f32_e32 v78, v78
	v_exp_f32_e32 v79, v79
	v_exp_f32_e32 v80, v80
	v_exp_f32_e32 v81, v81
	v_pk_add_f32 v[188:189], v[66:67], v[68:69]
	v_pk_add_f32 v[190:191], v[70:71], v[72:73]
	v_pk_add_f32 v[188:189], v[188:189], v[74:75]
	v_pk_add_f32 v[190:191], v[190:191], v[76:77]
	v_pk_add_f32 v[188:189], v[188:189], v[78:79]
	v_pk_add_f32 v[190:191], v[190:191], v[80:81]
	v_cvt_pk_bf16_f32 v66, v66, v67
	v_cvt_pk_bf16_f32 v67, v68, v69
	v_cvt_pk_bf16_f32 v68, v70, v71
	v_cvt_pk_bf16_f32 v69, v72, v73
	v_cvt_pk_bf16_f32 v70, v74, v75
	v_cvt_pk_bf16_f32 v71, v76, v77
	v_cvt_pk_bf16_f32 v72, v78, v79
	v_cvt_pk_bf16_f32 v73, v80, v81
	ds_read_b64_tr_b16 v[74:75], v156 offset:23552
	ds_read_b64_tr_b16 v[76:77], v156 offset:26112
	ds_read_b64_tr_b16 v[78:79], v156 offset:23616
	ds_read_b64_tr_b16 v[80:81], v156 offset:26176
	ds_read_b64_tr_b16 v[244:245], v156 offset:23680
	ds_read_b64_tr_b16 v[246:247], v156 offset:26240
	ds_read_b64_tr_b16 v[248:249], v156 offset:23744
	ds_read_b64_tr_b16 v[250:251], v156 offset:26304
	s_waitcnt lgkmcnt(8)
	v_mfma_f32_32x32x16_bf16 v[50:65], v[166:169], v[66:69], v[50:65]
	v_mfma_f32_32x32x16_bf16 v[34:49], v[176:179], v[66:69], v[34:49]
	v_mfma_f32_32x32x16_bf16 v[18:33], v[180:183], v[66:69], v[18:33]
	v_mfma_f32_32x32x16_bf16 v[2:17], v[184:187], v[66:69], v[2:17]
	ds_read_b64_tr_b16 v[166:167], v156 offset:28672
	ds_read_b64_tr_b16 v[168:169], v156 offset:31232
	ds_read_b64_tr_b16 v[176:177], v156 offset:28736
	ds_read_b64_tr_b16 v[178:179], v156 offset:31296
	ds_read_b64_tr_b16 v[180:181], v156 offset:28800
	ds_read_b64_tr_b16 v[182:183], v156 offset:31360
	ds_read_b64_tr_b16 v[184:185], v156 offset:28864
	ds_read_b64_tr_b16 v[186:187], v156 offset:31424
	v_pk_add_f32 v[82:83], v[82:83], v[164:165] op_sel_hi:[1,0]
	v_pk_add_f32 v[84:85], v[84:85], v[164:165] op_sel_hi:[1,0]
	v_pk_add_f32 v[86:87], v[86:87], v[164:165] op_sel_hi:[1,0]
	v_pk_add_f32 v[88:89], v[88:89], v[164:165] op_sel_hi:[1,0]
	v_pk_add_f32 v[90:91], v[90:91], v[164:165] op_sel_hi:[1,0]
	v_pk_add_f32 v[92:93], v[92:93], v[164:165] op_sel_hi:[1,0]
	v_pk_add_f32 v[94:95], v[94:95], v[164:165] op_sel_hi:[1,0]
	v_pk_add_f32 v[96:97], v[96:97], v[164:165] op_sel_hi:[1,0]
	v_exp_f32_e32 v82, v82
	v_exp_f32_e32 v83, v83
	v_exp_f32_e32 v84, v84
	v_exp_f32_e32 v85, v85
	v_exp_f32_e32 v86, v86
	v_exp_f32_e32 v87, v87
	v_exp_f32_e32 v88, v88
	v_exp_f32_e32 v89, v89
	v_exp_f32_e32 v90, v90
	v_exp_f32_e32 v91, v91
	v_exp_f32_e32 v92, v92
	v_exp_f32_e32 v93, v93
	v_exp_f32_e32 v94, v94
	v_exp_f32_e32 v95, v95
	v_exp_f32_e32 v96, v96
	v_exp_f32_e32 v97, v97
	v_pk_add_f32 v[188:189], v[188:189], v[82:83]
	v_pk_add_f32 v[190:191], v[190:191], v[84:85]
	v_pk_add_f32 v[188:189], v[188:189], v[86:87]
	v_pk_add_f32 v[190:191], v[190:191], v[88:89]
	v_pk_add_f32 v[188:189], v[188:189], v[90:91]
	v_pk_add_f32 v[190:191], v[190:191], v[92:93]
	v_pk_add_f32 v[188:189], v[188:189], v[94:95]
	v_pk_add_f32 v[190:191], v[190:191], v[96:97]
	v_cvt_pk_bf16_f32 v82, v82, v83
	v_cvt_pk_bf16_f32 v83, v84, v85
	v_cvt_pk_bf16_f32 v84, v86, v87
	v_cvt_pk_bf16_f32 v85, v88, v89
	v_cvt_pk_bf16_f32 v86, v90, v91
	v_cvt_pk_bf16_f32 v87, v92, v93
	v_cvt_pk_bf16_f32 v88, v94, v95
	v_cvt_pk_bf16_f32 v89, v96, v97
	v_pk_add_f32 v[188:189], v[188:189], v[190:191]
	s_waitcnt lgkmcnt(8)
	v_mfma_f32_32x32x16_bf16 v[50:65], v[74:77], v[70:73], v[50:65]
	v_mfma_f32_32x32x16_bf16 v[34:49], v[78:81], v[70:73], v[34:49]
	v_mfma_f32_32x32x16_bf16 v[18:33], v[244:247], v[70:73], v[18:33]
	v_mfma_f32_32x32x16_bf16 v[2:17], v[248:251], v[70:73], v[2:17]
	ds_read_b64_tr_b16 v[74:75], v156 offset:33792
	ds_read_b64_tr_b16 v[76:77], v156 offset:36352
	ds_read_b64_tr_b16 v[78:79], v156 offset:33856
	ds_read_b64_tr_b16 v[80:81], v156 offset:36416
	ds_read_b64_tr_b16 v[244:245], v156 offset:33920
	ds_read_b64_tr_b16 v[246:247], v156 offset:36480
	ds_read_b64_tr_b16 v[248:249], v156 offset:33984
	ds_read_b64_tr_b16 v[250:251], v156 offset:36544
	v_add_f32_e32 v0, v188, v189
	v_add_f32_e32 v159, v159, v0
	s_waitcnt lgkmcnt(8)
	v_mfma_f32_32x32x16_bf16 v[50:65], v[166:169], v[82:85], v[50:65]
	v_mfma_f32_32x32x16_bf16 v[34:49], v[176:179], v[82:85], v[34:49]
	v_mfma_f32_32x32x16_bf16 v[18:33], v[180:183], v[82:85], v[18:33]
	v_mfma_f32_32x32x16_bf16 v[2:17], v[184:187], v[82:85], v[2:17]
	s_waitcnt lgkmcnt(0)
	v_mfma_f32_32x32x16_bf16 v[50:65], v[74:77], v[86:89], v[50:65]
	v_mfma_f32_32x32x16_bf16 v[34:49], v[78:81], v[86:89], v[34:49]
	v_mfma_f32_32x32x16_bf16 v[18:33], v[244:247], v[86:89], v[18:33]
	v_mfma_f32_32x32x16_bf16 v[2:17], v[248:251], v[86:89], v[2:17]
	s_branch .LBB0_931
; __device__ __forceinline__ float fexp2(float x) { return __builtin_amdgcn_exp2f(x); }
; template <int NEB>
; __device__ __forceinline__ void softmax_tile(f32x16& X0, f32x16& X1, float& m, float& l, f32x16 (&OT)[NEB]) {
;     float mx = X0[0];
; #pragma unroll
;     for (int r = 1; r < 16; ++r) mx = fmaxf(mx, X0[r]);
; #pragma unroll
;     for (int r = 0; r < 16; ++r) mx = fmaxf(mx, X1[r]);
;     mx = fmaxf(mx, __shfl_xor(mx, 32));
;     if (__any(mx > m + 8.f)) {
;         const float mn = fmaxf(m, mx), alpha = fexp2(m - mn); m = mn; l *= alpha;
; #pragma unroll
;         for (int e = 0; e < NEB; ++e) OT[e] = OT[e] * alpha;
;     }
.Lpf0_slow:
	ds_read_b128 v[66:69], v162
	ds_read_b128 v[166:169], v162 offset:32
	ds_read_b128 v[82:85], v162 offset:4608
	ds_read_b128 v[176:179], v162 offset:4640
	v_cvt_f32_i32_e32 v186, v158
	s_waitcnt lgkmcnt(3)
	v_mfma_f32_32x32x16_bf16 v[66:81], v[66:69], v[110:113], 0
	v_add_f32_e32 v187, 0xc2000000, v186
	v_add_f32_e32 v0, -1.0, v186
	s_waitcnt lgkmcnt(1)
	v_mfma_f32_32x32x16_bf16 v[82:97], v[82:85], v[110:113], 0
	v_mfma_f32_32x32x16_bf16 v[66:81], v[166:169], v[106:109], v[66:81]
	s_waitcnt lgkmcnt(0)
	v_mfma_f32_32x32x16_bf16 v[82:97], v[176:179], v[106:109], v[82:97]
	ds_read_b128 v[166:169], v162 offset:64
	ds_read_b128 v[176:179], v162 offset:96
	s_waitcnt lgkmcnt(1)
	v_mfma_f32_32x32x16_bf16 v[66:81], v[166:169], v[102:105], v[66:81]
	ds_read_b128 v[166:169], v162 offset:4672
	ds_read_b128 v[182:185], v162 offset:4704
	s_waitcnt lgkmcnt(1)
	v_mfma_f32_32x32x16_bf16 v[82:97], v[166:169], v[102:105], v[82:97]
	v_mfma_f32_32x32x16_bf16 v[66:81], v[176:179], v[98:101], v[66:81]
	s_waitcnt lgkmcnt(0)
	v_mfma_f32_32x32x16_bf16 v[82:97], v[182:185], v[98:101], v[82:97]
	s_nop 9
	v_fma_f32 v180, -v153, |v186|, v66
	v_add_f32_e32 v66, -1.0, v187
	v_fma_f32 v0, -v153, |v0|, v67
	v_add_f32_e32 v67, 0xc1d80000, v186
	v_fma_f32 v179, -v153, |v66|, v83
	v_add_f32_e32 v66, -2.0, v186
	v_fma_f32 v177, -v153, |v66|, v68
	v_add_f32_e32 v66, -2.0, v187
	v_fma_f32 v178, -v153, |v66|, v84
	v_add_f32_e32 v66, 0xc0400000, v186
	v_fma_f32 v175, -v153, |v66|, v69
	v_add_f32_e32 v66, 0xc0400000, v187
	v_fma_f32 v176, -v153, |v66|, v85
	v_add_f32_e32 v66, 0xc1000000, v186
	v_fma_f32 v168, -v153, |v66|, v70
	v_add_f32_e32 v66, 0xc1000000, v187
	v_fma_f32 v169, -v153, |v66|, v86
	v_add_f32_e32 v66, 0xc1100000, v186
	v_fma_f32 v166, -v153, |v66|, v71
	v_add_f32_e32 v66, 0xc1100000, v187
	v_fma_f32 v167, -v153, |v66|, v87
	v_add_f32_e32 v66, 0xc1200000, v186
	v_fma_f32 v151, -v153, |v66|, v72
	v_add_f32_e32 v66, 0xc1200000, v187
	v_fma_f32 v164, -v153, |v66|, v88
	v_add_f32_e32 v66, 0xc1300000, v186
	v_fma_f32 v87, -v153, |v66|, v73
	v_add_f32_e32 v66, 0xc1300000, v187
	v_fma_f32 v88, -v153, |v66|, v89
	v_add_f32_e32 v66, 0xc1800000, v186
	v_fma_f32 v85, -v153, |v66|, v74
	v_add_f32_e32 v66, 0xc1800000, v187
	v_fma_f32 v86, -v153, |v66|, v90
	v_add_f32_e32 v66, 0xc1880000, v186
	v_fma_f32 v83, -v153, |v66|, v75
	v_add_f32_e32 v66, 0xc1880000, v187
	v_fma_f32 v84, -v153, |v66|, v91
	v_add_f32_e32 v66, 0xc1900000, v186
	v_fma_f32 v76, -v153, |v66|, v76
	v_add_f32_e32 v66, 0xc1900000, v187
	v_fma_f32 v181, -v153, |v187|, v82
	v_fma_f32 v82, -v153, |v66|, v92
	v_add_f32_e32 v66, 0xc1980000, v186
	v_fma_f32 v74, -v153, |v66|, v77
	v_add_f32_e32 v66, 0xc1980000, v187
	v_max_f32_e32 v77, v180, v0
	v_fma_f32 v75, -v153, |v66|, v93
	v_add_f32_e32 v66, 0xc1c00000, v186
	v_max3_f32 v77, v77, v177, v175
	v_fma_f32 v73, -v153, |v66|, v78
	v_add_f32_e32 v66, 0xc1c00000, v187
	v_max3_f32 v77, v77, v168, v166
	v_fma_f32 v70, -v153, |v66|, v94
	v_add_f32_e32 v66, 0xc1c80000, v186
	v_max3_f32 v77, v77, v151, v87
	v_fma_f32 v71, -v153, |v66|, v79
	v_add_f32_e32 v66, 0xc1c80000, v187
	v_max3_f32 v77, v77, v85, v83
	v_fma_f32 v72, -v153, |v66|, v95
	v_add_f32_e32 v66, 0xc1d00000, v186
	v_max3_f32 v77, v77, v76, v74
	v_fma_f32 v68, -v153, |v66|, v80
	v_fma_f32 v69, -v153, |v67|, v81
	v_max3_f32 v77, v77, v73, v71
	v_max3_f32 v77, v77, v68, v69
	v_max3_f32 v77, v77, v181, v179
	v_max3_f32 v77, v77, v178, v176
	v_max3_f32 v77, v77, v169, v167
	v_max3_f32 v77, v77, v164, v88
	v_max3_f32 v77, v77, v86, v84
	v_add_f32_e32 v66, 0xc1d00000, v187
	v_add_f32_e32 v67, 0xc1d80000, v187
	v_max3_f32 v77, v77, v82, v75
	v_fma_f32 v66, -v153, |v66|, v96
	v_fma_f32 v67, -v153, |v67|, v97
	v_max3_f32 v77, v77, v70, v72
	v_max3_f32 v77, v77, v66, v67
	ds_bpermute_b32 v78, v171, v77
	s_waitcnt lgkmcnt(0)
	v_max_f32_e32 v78, v78, v78
	v_max_f32_e32 v77, v77, v78
	v_add_f32_e32 v78, 0x41000000, v163
	v_cmp_gt_f32_e32 vcc, v77, v78
	s_cbranch_vccz .LBB0_930
	v_max_f32_e32 v77, v77, v77
	v_max_f32_e32 v78, v163, v163
	v_max_f32_e32 v77, v78, v77
	v_sub_f32_e32 v78, v163, v77
	v_exp_f32_e32 v78, v78
	v_mov_b32_e32 v163, v77
	v_mul_f32_e32 v159, v159, v78
	v_pk_mul_f32 v[64:65], v[64:65], v[78:79] op_sel_hi:[1,0]
	v_pk_mul_f32 v[62:63], v[62:63], v[78:79] op_sel_hi:[1,0]
	v_pk_mul_f32 v[60:61], v[60:61], v[78:79] op_sel_hi:[1,0]
	v_pk_mul_f32 v[58:59], v[58:59], v[78:79] op_sel_hi:[1,0]
	v_pk_mul_f32 v[56:57], v[56:57], v[78:79] op_sel_hi:[1,0]
	v_pk_mul_f32 v[54:55], v[54:55], v[78:79] op_sel_hi:[1,0]
	v_pk_mul_f32 v[52:53], v[52:53], v[78:79] op_sel_hi:[1,0]
	v_pk_mul_f32 v[50:51], v[50:51], v[78:79] op_sel_hi:[1,0]
	v_pk_mul_f32 v[48:49], v[48:49], v[78:79] op_sel_hi:[1,0]
	v_pk_mul_f32 v[46:47], v[46:47], v[78:79] op_sel_hi:[1,0]
	v_pk_mul_f32 v[44:45], v[44:45], v[78:79] op_sel_hi:[1,0]
	v_pk_mul_f32 v[42:43], v[42:43], v[78:79] op_sel_hi:[1,0]
	v_pk_mul_f32 v[40:41], v[40:41], v[78:79] op_sel_hi:[1,0]
	v_pk_mul_f32 v[38:39], v[38:39], v[78:79] op_sel_hi:[1,0]
	v_pk_mul_f32 v[36:37], v[36:37], v[78:79] op_sel_hi:[1,0]
	v_pk_mul_f32 v[34:35], v[34:35], v[78:79] op_sel_hi:[1,0]
	v_pk_mul_f32 v[32:33], v[32:33], v[78:79] op_sel_hi:[1,0]
	v_pk_mul_f32 v[30:31], v[30:31], v[78:79] op_sel_hi:[1,0]
	v_pk_mul_f32 v[28:29], v[28:29], v[78:79] op_sel_hi:[1,0]
	v_pk_mul_f32 v[26:27], v[26:27], v[78:79] op_sel_hi:[1,0]
	v_pk_mul_f32 v[24:25], v[24:25], v[78:79] op_sel_hi:[1,0]
	v_pk_mul_f32 v[22:23], v[22:23], v[78:79] op_sel_hi:[1,0]
	v_pk_mul_f32 v[20:21], v[20:21], v[78:79] op_sel_hi:[1,0]
	v_pk_mul_f32 v[18:19], v[18:19], v[78:79] op_sel_hi:[1,0]
	v_pk_mul_f32 v[16:17], v[16:17], v[78:79] op_sel_hi:[1,0]
	v_pk_mul_f32 v[14:15], v[14:15], v[78:79] op_sel_hi:[1,0]
	v_pk_mul_f32 v[12:13], v[12:13], v[78:79] op_sel_hi:[1,0]
	v_pk_mul_f32 v[10:11], v[10:11], v[78:79] op_sel_hi:[1,0]
	v_pk_mul_f32 v[8:9], v[8:9], v[78:79] op_sel_hi:[1,0]
	v_pk_mul_f32 v[6:7], v[6:7], v[78:79] op_sel_hi:[1,0]
	v_pk_mul_f32 v[4:5], v[4:5], v[78:79] op_sel_hi:[1,0]
	v_pk_mul_f32 v[2:3], v[2:3], v[78:79] op_sel_hi:[1,0]

; __device__ __forceinline__ float fexp2(float x) { return __builtin_amdgcn_exp2f(x); }
; template <int NEB>
; __device__ __forceinline__ void softmax_tile(f32x16& X0, f32x16& X1, float& m, float& l, f32x16 (&OT)[NEB]) {
;     float mx = X0[0];
; #pragma unroll
;     for (int r = 1; r < 16; ++r) mx = fmaxf(mx, X0[r]);
; #pragma unroll
;     for (int r = 0; r < 16; ++r) mx = fmaxf(mx, X1[r]);
;     mx = fmaxf(mx, __shfl_xor(mx, 32));
;     if (__any(mx > m + 8.f)) {
;         const float mn = fmaxf(m, mx), alpha = fexp2(m - mn); m = mn; l *= alpha;
; #pragma unroll
;         for (int e = 0; e < NEB; ++e) OT[e] = OT[e] * alpha;
;     }
.LBB0_935:
	s_add_i32 s99, s28, 1
	s_cmp_ge_u32 s99, s14
	s_cbranch_scc1 .Lpf1_slow
	ds_read_b128 v[66:69], v162 offset:38912
	ds_read_b128 v[166:169], v162 offset:38944
	ds_read_b128 v[82:85], v162 offset:43520
	ds_read_b128 v[176:179], v162 offset:43552
	v_subrev_u32_e32 v0, 64, v158
	v_cvt_f32_i32_e32 v186, v0
	s_waitcnt lgkmcnt(3)
	v_mfma_f32_32x32x16_bf16 v[66:81], v[66:69], v[110:113], v[210:225]
	v_mul_f32_e64 v175, -v153, v186
	s_waitcnt lgkmcnt(1)
	v_mfma_f32_32x32x16_bf16 v[82:97], v[82:85], v[110:113], v[226:241]
	v_mfma_f32_32x32x16_bf16 v[66:81], v[166:169], v[106:109], v[66:81]
	s_waitcnt lgkmcnt(0)
	v_mfma_f32_32x32x16_bf16 v[82:97], v[176:179], v[106:109], v[82:97]
	ds_read_b128 v[166:169], v162 offset:38976
	ds_read_b128 v[176:179], v162 offset:39008
	s_waitcnt lgkmcnt(1)
	v_mfma_f32_32x32x16_bf16 v[66:81], v[166:169], v[102:105], v[66:81]
	ds_read_b128 v[166:169], v162 offset:43584
	ds_read_b128 v[182:185], v162 offset:43616
	s_waitcnt lgkmcnt(1)
	v_mfma_f32_32x32x16_bf16 v[82:97], v[166:169], v[102:105], v[82:97]
	v_mfma_f32_32x32x16_bf16 v[66:81], v[176:179], v[98:101], v[66:81]
	s_waitcnt lgkmcnt(0)
	v_mfma_f32_32x32x16_bf16 v[82:97], v[182:185], v[98:101], v[82:97]
	ds_read_b64_tr_b16 v[166:167], v156 offset:57344
	ds_read_b64_tr_b16 v[168:169], v156 offset:59904
	ds_read_b64_tr_b16 v[176:177], v156 offset:57408
	ds_read_b64_tr_b16 v[178:179], v156 offset:59968
	ds_read_b64_tr_b16 v[180:181], v156 offset:57472
	ds_read_b64_tr_b16 v[182:183], v156 offset:60032
	ds_read_b64_tr_b16 v[184:185], v156 offset:57536
	ds_read_b64_tr_b16 v[186:187], v156 offset:60096
	s_nop 5
	v_max3_f32 v0, v66, v67, v68
	v_max3_f32 v151, v82, v83, v84
	v_max3_f32 v0, v0, v69, v70
	v_max3_f32 v151, v151, v85, v86
	v_max3_f32 v0, v0, v71, v72
	v_max3_f32 v151, v151, v87, v88
	v_max3_f32 v0, v0, v73, v74
	v_max3_f32 v151, v151, v89, v90
	v_max3_f32 v0, v0, v75, v76
	v_max3_f32 v151, v151, v91, v92
	v_max3_f32 v0, v0, v77, v78
	v_max3_f32 v151, v151, v93, v94
	v_max3_f32 v0, v0, v79, v80
	v_max3_f32 v151, v151, v95, v96
	v_max3_f32 v0, v0, v81, v151
	v_max_f32_e32 v0, v0, v97
	v_add_f32_e32 v0, v0, v175
	ds_bpermute_b32 v164, v171, v0
	s_waitcnt lgkmcnt(0)
	v_max_f32_e32 v0, v0, v164
	v_add_f32_e32 v164, 0x41000000, v163
	v_cmp_gt_f32_e32 vcc, v0, v164
	s_cbranch_vccz .Lpf1_nores
	v_max_f32_e32 v0, v163, v0
	v_sub_f32_e32 v164, v163, v0
	v_exp_f32_e32 v164, v164
	v_mov_b32_e32 v163, v0
	s_nop 0
	v_mul_f32_e32 v159, v159, v164
	v_pk_mul_f32 v[64:65], v[64:65], v[164:165] op_sel_hi:[1,0]
	v_pk_mul_f32 v[62:63], v[62:63], v[164:165] op_sel_hi:[1,0]
	v_pk_mul_f32 v[60:61], v[60:61], v[164:165] op_sel_hi:[1,0]
	v_pk_mul_f32 v[58:59], v[58:59], v[164:165] op_sel_hi:[1,0]
	v_pk_mul_f32 v[56:57], v[56:57], v[164:165] op_sel_hi:[1,0]
	v_pk_mul_f32 v[54:55], v[54:55], v[164:165] op_sel_hi:[1,0]
	v_pk_mul_f32 v[52:53], v[52:53], v[164:165] op_sel_hi:[1,0]
	v_pk_mul_f32 v[50:51], v[50:51], v[164:165] op_sel_hi:[1,0]
	v_pk_mul_f32 v[48:49], v[48:49], v[164:165] op_sel_hi:[1,0]
	v_pk_mul_f32 v[46:47], v[46:47], v[164:165] op_sel_hi:[1,0]
	v_pk_mul_f32 v[44:45], v[44:45], v[164:165] op_sel_hi:[1,0]
	v_pk_mul_f32 v[42:43], v[42:43], v[164:165] op_sel_hi:[1,0]
	v_pk_mul_f32 v[40:41], v[40:41], v[164:165] op_sel_hi:[1,0]
	v_pk_mul_f32 v[38:39], v[38:39], v[164:165] op_sel_hi:[1,0]
	v_pk_mul_f32 v[36:37], v[36:37], v[164:165] op_sel_hi:[1,0]
	v_pk_mul_f32 v[34:35], v[34:35], v[164:165] op_sel_hi:[1,0]
	v_pk_mul_f32 v[32:33], v[32:33], v[164:165] op_sel_hi:[1,0]
	v_pk_mul_f32 v[30:31], v[30:31], v[164:165] op_sel_hi:[1,0]
	v_pk_mul_f32 v[28:29], v[28:29], v[164:165] op_sel_hi:[1,0]
	v_pk_mul_f32 v[26:27], v[26:27], v[164:165] op_sel_hi:[1,0]
	v_pk_mul_f32 v[24:25], v[24:25], v[164:165] op_sel_hi:[1,0]
	v_pk_mul_f32 v[22:23], v[22:23], v[164:165] op_sel_hi:[1,0]
	v_pk_mul_f32 v[20:21], v[20:21], v[164:165] op_sel_hi:[1,0]
	v_pk_mul_f32 v[18:19], v[18:19], v[164:165] op_sel_hi:[1,0]
	v_pk_mul_f32 v[16:17], v[16:17], v[164:165] op_sel_hi:[1,0]
	v_pk_mul_f32 v[14:15], v[14:15], v[164:165] op_sel_hi:[1,0]
	v_pk_mul_f32 v[12:13], v[12:13], v[164:165] op_sel_hi:[1,0]
	v_pk_mul_f32 v[10:11], v[10:11], v[164:165] op_sel_hi:[1,0]
	v_pk_mul_f32 v[8:9], v[8:9], v[164:165] op_sel_hi:[1,0]
	v_pk_mul_f32 v[6:7], v[6:7], v[164:165] op_sel_hi:[1,0]
	v_pk_mul_f32 v[4:5], v[4:5], v[164:165] op_sel_hi:[1,0]
	v_pk_mul_f32 v[2:3], v[2:3], v[164:165] op_sel_hi:[1,0]
; #define LAS __attribute__((address_space(3)))
; __device__ __forceinline__ float fexp2(float x) { return __builtin_amdgcn_exp2f(x); }
; __device__ __forceinline__ s16x4 vtr(const LAS unsigned char* p) { return __builtin_bit_cast(s16x4, __builtin_amdgcn_ds_read_tr16_b64_v4i16((LAS v4i16_t*)p)); }
; __device__ __forceinline__ bf16x8 cat8(s16x4 lo, s16x4 hi) { return (bf16x8){lo[0], lo[1], lo[2], lo[3], hi[0], hi[1], hi[2], hi[3]}; }
; template <int NEB>
; __device__ __forceinline__ void softmax_tile(f32x16& X0, f32x16& X1, float& m, float& l, f32x16 (&OT)[NEB]) {
;     ...
;     float s = 0.f;
; #pragma unroll
;     for (int r = 0; r < 16; ++r) { X0[r] = fexp2(X0[r] - m); X1[r] = fexp2(X1[r] - m); s += X0[r] + X1[r]; }
;     l += s;
; }
; template <int VRS, int NEB, bool SB = false>
; __device__ __forceinline__ void pv_tile(f32x16 (&OT)[NEB], const f32x16& X0, const f32x16& X1, const LAS unsigned char* vlane  ) {
; #pragma unroll
;     for (int kk = 0; kk < 4; ++kk) {
;         const bf16x8 pa = packp(kk < 2 ? X0 : X1, (kk & 1) * 8);
; #pragma unroll
;         for (int eb = 0; eb < NEB; ++eb) {
;             const s16x4 lo = vtr(vlane + (kk * 16) * VRS + eb * 64), hi = vtr(vlane + (kk * 16 + 8) * VRS + eb * 64);
;             OT[eb] = __builtin_amdgcn_mfma_f32_32x32x16_bf16(cat8(lo, hi), pa, OT[eb], 0, 0, 0);
;         }
;         if (SB) __builtin_amdgcn_sched_barrier(0);
;     }
; }
.Lpf1_nores:
	v_sub_f32_e32 v164, v175, v163
	v_pk_add_f32 v[66:67], v[66:67], v[164:165] op_sel_hi:[1,0]
	v_pk_add_f32 v[68:69], v[68:69], v[164:165] op_sel_hi:[1,0]
	v_pk_add_f32 v[70:71], v[70:71], v[164:165] op_sel_hi:[1,0]
	v_pk_add_f32 v[72:73], v[72:73], v[164:165] op_sel_hi:[1,0]
	v_pk_add_f32 v[74:75], v[74:75], v[164:165] op_sel_hi:[1,0]
	v_pk_add_f32 v[76:77], v[76:77], v[164:165] op_sel_hi:[1,0]
	v_pk_add_f32 v[78:79], v[78:79], v[164:165] op_sel_hi:[1,0]
	v_pk_add_f32 v[80:81], v[80:81], v[164:165] op_sel_hi:[1,0]
	v_exp_f32_e32 v66, v66
	v_exp_f32_e32 v67, v67
	v_exp_f32_e32 v68, v68
	v_exp_f32_e32 v69, v69
	v_exp_f32_e32 v70, v70
	v_exp_f32_e32 v71, v71
	v_exp_f32_e32 v72, v72
	v_exp_f32_e32 v73, v73
	v_exp_f32_e32 v74, v74
	v_exp_f32_e32 v75, v75
	v_exp_f32_e32 v76, v76
	v_exp_f32_e32 v77, v77
	v_exp_f32_e32 v78, v78
	v_exp_f32_e32 v79, v79
	v_exp_f32_e32 v80, v80
	v_exp_f32_e32 v81, v81
	v_pk_add_f32 v[188:189], v[66:67], v[68:69]
	v_pk_add_f32 v[190:191], v[70:71], v[72:73]
	v_pk_add_f32 v[188:189], v[188:189], v[74:75]
	v_pk_add_f32 v[190:191], v[190:191], v[76:77]
	v_pk_add_f32 v[188:189], v[188:189], v[78:79]
	v_pk_add_f32 v[190:191], v[190:191], v[80:81]
	v_cvt_pk_bf16_f32 v66, v66, v67
	v_cvt_pk_bf16_f32 v67, v68, v69
	v_cvt_pk_bf16_f32 v68, v70, v71
	v_cvt_pk_bf16_f32 v69, v72, v73
	v_cvt_pk_bf16_f32 v70, v74, v75
	v_cvt_pk_bf16_f32 v71, v76, v77
	v_cvt_pk_bf16_f32 v72, v78, v79
	v_cvt_pk_bf16_f32 v73, v80, v81
	ds_read_b64_tr_b16 v[74:75], v156 offset:62464
	ds_read_b64_tr_b16 v[76:77], v156 offset:65024
	ds_read_b64_tr_b16 v[78:79], v156 offset:62528
	ds_read_b64_tr_b16 v[80:81], v156 offset:65088
	ds_read_b64_tr_b16 v[244:245], v156 offset:62592
	ds_read_b64_tr_b16 v[246:247], v156 offset:65152
	ds_read_b64_tr_b16 v[248:249], v156 offset:62656
	ds_read_b64_tr_b16 v[250:251], v156 offset:65216
	s_waitcnt lgkmcnt(8)
	v_mfma_f32_32x32x16_bf16 v[50:65], v[166:169], v[66:69], v[50:65]
	v_mfma_f32_32x32x16_bf16 v[34:49], v[176:179], v[66:69], v[34:49]
	v_mfma_f32_32x32x16_bf16 v[18:33], v[180:183], v[66:69], v[18:33]
	v_mfma_f32_32x32x16_bf16 v[2:17], v[184:187], v[66:69], v[2:17]
	ds_read_b64_tr_b16 v[166:167], v157 offset:10240
	ds_read_b64_tr_b16 v[168:169], v157 offset:12800
	ds_read_b64_tr_b16 v[176:177], v157 offset:10304
	ds_read_b64_tr_b16 v[178:179], v157 offset:12864
	ds_read_b64_tr_b16 v[180:181], v157 offset:10368
	ds_read_b64_tr_b16 v[182:183], v157 offset:12928
	ds_read_b64_tr_b16 v[184:185], v157 offset:10432
	ds_read_b64_tr_b16 v[186:187], v157 offset:12992
	v_pk_add_f32 v[82:83], v[82:83], v[164:165] op_sel_hi:[1,0]
	v_pk_add_f32 v[84:85], v[84:85], v[164:165] op_sel_hi:[1,0]
	v_pk_add_f32 v[86:87], v[86:87], v[164:165] op_sel_hi:[1,0]
	v_pk_add_f32 v[88:89], v[88:89], v[164:165] op_sel_hi:[1,0]
	v_pk_add_f32 v[90:91], v[90:91], v[164:165] op_sel_hi:[1,0]
	v_pk_add_f32 v[92:93], v[92:93], v[164:165] op_sel_hi:[1,0]
	v_pk_add_f32 v[94:95], v[94:95], v[164:165] op_sel_hi:[1,0]
	v_pk_add_f32 v[96:97], v[96:97], v[164:165] op_sel_hi:[1,0]
	v_exp_f32_e32 v82, v82
	v_exp_f32_e32 v83, v83
	v_exp_f32_e32 v84, v84
	v_exp_f32_e32 v85, v85
	v_exp_f32_e32 v86, v86
	v_exp_f32_e32 v87, v87
	v_exp_f32_e32 v88, v88
	v_exp_f32_e32 v89, v89
	v_exp_f32_e32 v90, v90
	v_exp_f32_e32 v91, v91
	v_exp_f32_e32 v92, v92
	v_exp_f32_e32 v93, v93
	v_exp_f32_e32 v94, v94
	v_exp_f32_e32 v95, v95
	v_exp_f32_e32 v96, v96
	v_exp_f32_e32 v97, v97
	v_pk_add_f32 v[188:189], v[188:189], v[82:83]
	v_pk_add_f32 v[190:191], v[190:191], v[84:85]
	v_pk_add_f32 v[188:189], v[188:189], v[86:87]
	v_pk_add_f32 v[190:191], v[190:191], v[88:89]
	v_pk_add_f32 v[188:189], v[188:189], v[90:91]
	v_pk_add_f32 v[190:191], v[190:191], v[92:93]
	v_pk_add_f32 v[188:189], v[188:189], v[94:95]
	v_pk_add_f32 v[190:191], v[190:191], v[96:97]
	v_cvt_pk_bf16_f32 v82, v82, v83
	v_cvt_pk_bf16_f32 v83, v84, v85
	v_cvt_pk_bf16_f32 v84, v86, v87
	v_cvt_pk_bf16_f32 v85, v88, v89
	v_cvt_pk_bf16_f32 v86, v90, v91
	v_cvt_pk_bf16_f32 v87, v92, v93
	v_cvt_pk_bf16_f32 v88, v94, v95
	v_cvt_pk_bf16_f32 v89, v96, v97
	v_pk_add_f32 v[188:189], v[188:189], v[190:191]
	s_waitcnt lgkmcnt(8)
	v_mfma_f32_32x32x16_bf16 v[50:65], v[74:77], v[70:73], v[50:65]
	v_mfma_f32_32x32x16_bf16 v[34:49], v[78:81], v[70:73], v[34:49]
	v_mfma_f32_32x32x16_bf16 v[18:33], v[244:247], v[70:73], v[18:33]
	v_mfma_f32_32x32x16_bf16 v[2:17], v[248:251], v[70:73], v[2:17]
	ds_read_b64_tr_b16 v[74:75], v157 offset:15360
	ds_read_b64_tr_b16 v[76:77], v157 offset:17920
	ds_read_b64_tr_b16 v[78:79], v157 offset:15424
	ds_read_b64_tr_b16 v[80:81], v157 offset:17984
	ds_read_b64_tr_b16 v[244:245], v157 offset:15488
	ds_read_b64_tr_b16 v[246:247], v157 offset:18048
	ds_read_b64_tr_b16 v[248:249], v157 offset:15552
	ds_read_b64_tr_b16 v[250:251], v157 offset:18112
	v_add_f32_e32 v0, v188, v189
	v_add_f32_e32 v159, v159, v0
	s_waitcnt lgkmcnt(8)
	v_mfma_f32_32x32x16_bf16 v[50:65], v[166:169], v[82:85], v[50:65]
	v_mfma_f32_32x32x16_bf16 v[34:49], v[176:179], v[82:85], v[34:49]
	v_mfma_f32_32x32x16_bf16 v[18:33], v[180:183], v[82:85], v[18:33]
	v_mfma_f32_32x32x16_bf16 v[2:17], v[184:187], v[82:85], v[2:17]
	s_waitcnt lgkmcnt(0)
	v_mfma_f32_32x32x16_bf16 v[50:65], v[74:77], v[86:89], v[50:65]
	v_mfma_f32_32x32x16_bf16 v[34:49], v[78:81], v[86:89], v[34:49]
	v_mfma_f32_32x32x16_bf16 v[18:33], v[244:247], v[86:89], v[18:33]
	v_mfma_f32_32x32x16_bf16 v[2:17], v[248:251], v[86:89], v[2:17]
	s_branch .Lpf1_end

; #define LAS __attribute__((address_space(3)))
; __device__ __forceinline__ float fexp2(float x) { return __builtin_amdgcn_exp2f(x); }
; __device__ __forceinline__ s16x4 vtr(const LAS unsigned char* p) { return __builtin_bit_cast(s16x4, __builtin_amdgcn_ds_read_tr16_b64_v4i16((LAS v4i16_t*)p)); }
; __device__ __forceinline__ bf16x8 cat8(s16x4 lo, s16x4 hi) { return (bf16x8){lo[0], lo[1], lo[2], lo[3], hi[0], hi[1], hi[2], hi[3]}; }
; template <int NEB>
; __device__ __forceinline__ void softmax_tile(f32x16& X0, f32x16& X1, float& m, float& l, f32x16 (&OT)[NEB]) {
;     ...
;     float s = 0.f;
; #pragma unroll
;     for (int r = 0; r < 16; ++r) { X0[r] = fexp2(X0[r] - m); X1[r] = fexp2(X1[r] - m); s += X0[r] + X1[r]; }
;     l += s;
; }
; template <int VRS, int NEB, bool SB = false>
; __device__ __forceinline__ void pv_tile(f32x16 (&OT)[NEB], const f32x16& X0, const f32x16& X1, const LAS unsigned char* vlane  ) {
; #pragma unroll
;     for (int kk = 0; kk < 4; ++kk) {
;         const bf16x8 pa = packp(kk < 2 ? X0 : X1, (kk & 1) * 8);
; #pragma unroll
;         for (int eb = 0; eb < NEB; ++eb) {
;             const s16x4 lo = vtr(vlane + (kk * 16) * VRS + eb * 64), hi = vtr(vlane + (kk * 16 + 8) * VRS + eb * 64);
;             OT[eb] = __builtin_amdgcn_mfma_f32_32x32x16_bf16(cat8(lo, hi), pa, OT[eb], 0, 0, 0);
;         }
;         if (SB) __builtin_amdgcn_sched_barrier(0);
;     }
; }
;     ...
;     for (int tt = 0; tt < NT; tt += 2) {
;         if (tt + 2 < NT) DA_ISSUE(pfB, tt + 2);
;         DA_COMPUTE(tt, 0);
;         if (tt + 1 < NT) DA_WRITE(pfA, tt + 1, 1);
;         __syncthreads();
;         if (tt + 1 >= NT) break;
;         if (tt + 3 < NT) DA_ISSUE(pfA, tt + 3);
;         DA_COMPUTE(tt + 1, 1);
;         if (tt + 2 < NT) DA_WRITE(pfB, tt + 2, 0);
;         __syncthreads();
;     }
.LBB0_937:
	v_sub_f32_e32 v77, v180, v163
	v_sub_f32_e32 v78, v181, v163
	v_exp_f32_e32 v77, v77
	v_exp_f32_e32 v186, v78
	v_sub_f32_e32 v0, v0, v163
	v_sub_f32_e32 v78, v179, v163
	v_exp_f32_e32 v0, v0
	v_exp_f32_e32 v94, v78
	v_add_f32_e32 v95, v186, v77
	v_sub_f32_e32 v80, v176, v163
	v_exp_f32_e32 v96, v80
	v_pk_add_f32 v[78:79], v[94:95], v[0:1]
	v_sub_f32_e32 v76, v76, v163
	v_pk_add_f32 v[78:79], v[78:79], v[78:79] op_sel_hi:[0,1]
	v_sub_f32_e32 v78, v177, v163
	v_exp_f32_e32 v89, v78
	v_sub_f32_e32 v78, v178, v163
	v_exp_f32_e32 v95, v78
	v_sub_f32_e32 v78, v175, v163
	v_exp_f32_e32 v78, v78
	v_sub_f32_e32 v74, v74, v163
	v_add_f32_e32 v97, v95, v89
	v_sub_f32_e32 v70, v70, v163
	v_pk_add_f32 v[80:81], v[96:97], v[78:79]
	v_sub_f32_e32 v79, v168, v163
	v_exp_f32_e32 v97, v79
	v_sub_f32_e32 v79, v169, v163
	v_pk_add_f32 v[90:91], v[80:81], v[80:81] op_sel_hi:[0,1]
	v_exp_f32_e32 v175, v79
	v_sub_f32_e32 v79, v166, v163
	v_exp_f32_e32 v90, v79
	v_sub_f32_e32 v79, v167, v163
	v_exp_f32_e32 v166, v79
	v_add_f32_e32 v167, v175, v97
	v_sub_f32_e32 v79, v151, v163
	v_sub_f32_e32 v68, v68, v163
	v_pk_add_f32 v[80:81], v[166:167], v[90:91]
	v_exp_f32_e32 v91, v79
	v_sub_f32_e32 v79, v164, v163
	v_pk_add_f32 v[92:93], v[80:81], v[80:81] op_sel_hi:[0,1]
	v_exp_f32_e32 v151, v79
	v_sub_f32_e32 v79, v87, v163
	v_exp_f32_e32 v92, v79
	v_sub_f32_e32 v79, v88, v163
	v_exp_f32_e32 v168, v79
	v_add_f32_e32 v169, v151, v91
	v_sub_f32_e32 v79, v85, v163
	v_exp_f32_e32 v164, v79
	v_pk_add_f32 v[80:81], v[168:169], v[92:93]
	v_sub_f32_e32 v79, v86, v163
	v_pk_add_f32 v[176:177], v[80:81], v[80:81] op_sel_hi:[0,1]
	v_exp_f32_e32 v167, v79
	v_sub_f32_e32 v79, v83, v163
	v_exp_f32_e32 v176, v79
	v_sub_f32_e32 v79, v84, v163
	v_exp_f32_e32 v178, v79
	v_add_f32_e32 v179, v167, v164
	v_exp_f32_e32 v169, v76
	v_sub_f32_e32 v76, v82, v163
	v_pk_add_f32 v[80:81], v[178:179], v[176:177]
	v_exp_f32_e32 v177, v76
	v_pk_add_f32 v[180:181], v[80:81], v[80:81] op_sel_hi:[0,1]
	v_sub_f32_e32 v179, v75, v163
	v_cvt_pk_bf16_f32 v75, v89, v78
	ds_read_b64_tr_b16 v[78:79], v156 offset:57344
	ds_read_b64_tr_b16 v[80:81], v156 offset:59904
	v_exp_f32_e32 v180, v74
	v_exp_f32_e32 v182, v179
	v_cvt_pk_bf16_f32 v74, v77, v0
	v_cvt_pk_bf16_f32 v76, v97, v90
	v_cvt_pk_bf16_f32 v77, v91, v92
	v_add_f32_e32 v183, v177, v169
	ds_read_b64_tr_b16 v[82:83], v156 offset:57408
	ds_read_b64_tr_b16 v[86:87], v156 offset:57472
	ds_read_b64_tr_b16 v[90:91], v156 offset:57536
	ds_read_b64_tr_b16 v[84:85], v156 offset:59968
	ds_read_b64_tr_b16 v[88:89], v156 offset:60032
	ds_read_b64_tr_b16 v[92:93], v156 offset:60096
	s_waitcnt lgkmcnt(6)
	v_mfma_f32_32x32x16_bf16 v[50:65], v[78:81], v[74:77], v[50:65]
	v_add_f32_e64 v78, v182, v180
	v_add_f32_e64 v79, v183, v181
	v_sub_f32_e32 v0, v73, v163
	v_pk_add_f32 v[78:79], v[78:79], v[78:79] op_sel_hi:[0,1]
	v_exp_f32_e32 v97, v70
	v_sub_f32_e32 v70, v71, v163
	v_exp_f32_e32 v0, v0
	v_exp_f32_e32 v78, v70
	v_sub_f32_e32 v70, v72, v163
	v_exp_f32_e32 v184, v70
	s_waitcnt lgkmcnt(2)
	v_mfma_f32_32x32x16_bf16 v[34:49], v[82:85], v[74:77], v[34:49]
	v_add_f32_e32 v185, v97, v0
	v_exp_f32_e32 v179, v68
	v_pk_add_f32 v[70:71], v[184:185], v[78:79]
	v_sub_f32_e32 v68, v69, v163
	v_cvt_pk_bf16_f32 v69, v169, v180
	s_waitcnt lgkmcnt(1)
	v_mfma_f32_32x32x16_bf16 v[18:33], v[86:89], v[74:77], v[18:33]
	v_add_f32_e64 v88, v70, v70
	v_add_f32_e64 v89, v70, v71
	v_exp_f32_e32 v88, v68
	v_cvt_pk_bf16_f32 v70, v0, v78
	v_cvt_pk_bf16_f32 v68, v164, v176
	v_sub_f32_e32 v0, v66, v163
	v_cvt_pk_bf16_f32 v71, v179, v88
	v_sub_f32_e32 v66, v67, v163
	s_waitcnt lgkmcnt(0)
	v_mfma_f32_32x32x16_bf16 v[2:17], v[90:93], v[74:77], v[2:17]
	ds_read_b64_tr_b16 v[72:73], v156 offset:62464
	ds_read_b64_tr_b16 v[74:75], v156 offset:65024
	ds_read_b64_tr_b16 v[76:77], v156 offset:62528
	ds_read_b64_tr_b16 v[80:81], v156 offset:62592
	ds_read_b64_tr_b16 v[84:85], v156 offset:62656
	ds_read_b64_tr_b16 v[78:79], v156 offset:65088
	ds_read_b64_tr_b16 v[82:83], v156 offset:65152
	ds_read_b64_tr_b16 v[86:87], v156 offset:65216
	v_exp_f32_e32 v0, v0
	v_exp_f32_e32 v90, v66
	v_cvt_pk_bf16_f32 v66, v167, v178
	v_cvt_pk_bf16_f32 v67, v177, v182
	v_add_f32_e32 v91, v0, v179
	s_waitcnt lgkmcnt(6)
	v_mfma_f32_32x32x16_bf16 v[50:65], v[72:75], v[68:71], v[50:65]
	ds_read_b64_tr_b16 v[72:73], v157 offset:10240
	ds_read_b64_tr_b16 v[74:75], v157 offset:12800
	s_waitcnt lgkmcnt(4)
	v_mfma_f32_32x32x16_bf16 v[34:49], v[76:79], v[68:71], v[34:49]
	s_waitcnt lgkmcnt(3)
	v_mfma_f32_32x32x16_bf16 v[18:33], v[80:83], v[68:71], v[18:33]
	s_waitcnt lgkmcnt(2)
	v_mfma_f32_32x32x16_bf16 v[2:17], v[84:87], v[68:71], v[2:17]
	ds_read_b64_tr_b16 v[76:77], v157 offset:10304
	ds_read_b64_tr_b16 v[80:81], v157 offset:10368
	ds_read_b64_tr_b16 v[84:85], v157 offset:10432
	ds_read_b64_tr_b16 v[78:79], v157 offset:12864
	ds_read_b64_tr_b16 v[82:83], v157 offset:12928
	ds_read_b64_tr_b16 v[86:87], v157 offset:12992
	v_cvt_pk_bf16_f32 v68, v186, v94
	v_cvt_pk_bf16_f32 v69, v95, v96
	v_cvt_pk_bf16_f32 v70, v175, v166
	v_cvt_pk_bf16_f32 v71, v151, v168
	s_waitcnt lgkmcnt(6)
	s_nop 0
	v_mfma_f32_32x32x16_bf16 v[50:65], v[72:75], v[68:71], v[50:65]
	s_waitcnt lgkmcnt(2)
	v_mfma_f32_32x32x16_bf16 v[34:49], v[76:79], v[68:71], v[34:49]
	s_waitcnt lgkmcnt(1)
	v_mfma_f32_32x32x16_bf16 v[18:33], v[80:83], v[68:71], v[18:33]
	s_waitcnt lgkmcnt(0)
	v_mfma_f32_32x32x16_bf16 v[2:17], v[84:87], v[68:71], v[2:17]
	ds_read_b64_tr_b16 v[70:71], v157 offset:15360
	ds_read_b64_tr_b16 v[72:73], v157 offset:17920
	ds_read_b64_tr_b16 v[74:75], v157 offset:15424
	ds_read_b64_tr_b16 v[78:79], v157 offset:15488
	ds_read_b64_tr_b16 v[82:83], v157 offset:15552
	ds_read_b64_tr_b16 v[76:77], v157 offset:17984
	ds_read_b64_tr_b16 v[80:81], v157 offset:18048
	ds_read_b64_tr_b16 v[84:85], v157 offset:18112
	v_cvt_pk_bf16_f32 v68, v97, v184
	v_cvt_pk_bf16_f32 v69, v0, v90
	s_waitcnt lgkmcnt(6)
	s_nop 0
	v_mfma_f32_32x32x16_bf16 v[50:65], v[70:73], v[66:69], v[50:65]
	v_add_f32_e64 v70, v90, v88
	v_add_f32_e64 v71, v91, v89
	v_add_f32_e32 v0, v70, v71
	v_add_f32_e32 v159, v159, v0
	s_waitcnt lgkmcnt(2)
	v_mfma_f32_32x32x16_bf16 v[34:49], v[74:77], v[66:69], v[34:49]
	s_waitcnt lgkmcnt(1)
	v_mfma_f32_32x32x16_bf16 v[18:33], v[78:81], v[66:69], v[18:33]
	s_waitcnt lgkmcnt(0)
	v_mfma_f32_32x32x16_bf16 v[2:17], v[82:85], v[66:69], v[2:17]
.Lpf1_end:
	s_andn2_b64 vcc, exec, s[6:7]
	s_cbranch_vccnz .LBB0_924
.LBB0_938:
	s_cmp_lg_u32 s9, 0
	s_cbranch_scc1 .LBB0_924
	s_cmp_ge_u32 s11, s13
	s_cbranch_scc1 .Lp_w2_all
	s_waitcnt vmcnt(4)
	s_branch .Lp_w2_done
